# P0 row loop arithmetic rewritten: packed f32 (v_pk_fma_f32) sum of squares and dot products, DPP-source adds, the 8 gate sums reduced jointly with permlane32/16 swaps + bank-masked DPP (17 instrs inst
# baseline (speedup 1.0000x reference)
.LBB0_110:
	v_lshlrev_b32_e32 v80, 12, v223
	s_add_i32 s0, 0, 0x18000
	v_and_b32_e32 v80, 0x7000, v80
	v_add_u32_e32 v80, s0, v80
	s_waitcnt vmcnt(14)
	v_mul_f32_e32 v64, v137, v172
	v_lshl_add_u32 v81, v135, 2, v80
	v_mul_f32_e32 v65, v139, v140
	ds_write_b32 v81, v64
	v_lshl_add_u32 v64, v136, 2, v80
	s_waitcnt vmcnt(13)
	v_mul_f32_e32 v66, v142, v171
	v_mul_f32_e32 v67, v143, v144
	ds_write_b32 v64, v65
	ds_write_b32 v81, v66 offset:512
	v_lshl_add_u32 v64, v138, 2, v80
	s_waitcnt vmcnt(12)
	v_mul_f32_e32 v68, v146, v170
	v_mul_f32_e32 v69, v147, v148
	ds_write_b32 v64, v67
	ds_write_b32 v81, v68 offset:1024
	v_lshl_add_u32 v64, v141, 2, v80
	s_waitcnt vmcnt(11)
	v_mul_f32_e32 v70, v150, v169
	v_mul_f32_e32 v71, v151, v152
	ds_write_b32 v64, v69
	ds_write_b32 v81, v70 offset:1536
	v_lshl_add_u32 v64, v145, 2, v80
	s_waitcnt vmcnt(10)
	v_mul_f32_e32 v72, v154, v167
	v_mul_f32_e32 v73, v155, v156
	ds_write_b32 v64, v71
	ds_write_b32 v81, v72 offset:2048
	v_lshl_add_u32 v64, v149, 2, v80
	s_waitcnt vmcnt(9)
	v_mul_f32_e32 v74, v158, v166
	v_mul_f32_e32 v75, v159, v160
	ds_write_b32 v64, v73
	ds_write_b32 v81, v74 offset:2560
	v_lshl_add_u32 v64, v153, 2, v80
	s_waitcnt vmcnt(8)
	v_mul_f32_e32 v76, v162, v165
	v_mul_f32_e32 v77, v163, v164
	ds_write_b32 v64, v75
	ds_write_b32 v81, v76 offset:3072
	v_lshl_add_u32 v64, v157, 2, v80
	s_waitcnt vmcnt(6)
	v_mul_f32_e32 v78, v173, v168
	s_waitcnt vmcnt(4)
	v_mul_f32_e32 v79, v174, v175
	ds_write_b32 v64, v77
	ds_write_b32 v81, v78 offset:3584
	v_lshl_add_u32 v64, v161, 2, v80
	s_and_b64 vcc, exec, s[10:11]
	v_lshlrev_b32_e32 v210, 3, v224
	ds_write_b32 v64, v79
	s_waitcnt lgkmcnt(0)
	s_barrier
	s_cbranch_vccz .LBB0_117
	v_mbcnt_lo_u32_b32 v64, -1, 0
	v_mbcnt_hi_u32_b32 v64, -1, v64
	v_and_b32_e32 v65, 64, v64
	v_add_u32_e32 v65, 64, v65
	v_xor_b32_e32 v66, 1, v64
	v_cmp_lt_i32_e32 vcc, v66, v65
	v_mov_b32_e32 v209, 0
	v_readlane_b32 s8, v252, 8
	v_cndmask_b32_e32 v66, v64, v66, vcc
	v_lshlrev_b32_e32 v225, 2, v66
	v_xor_b32_e32 v66, 2, v64
	v_cmp_lt_i32_e32 vcc, v66, v65
	v_readlane_b32 s16, v252, 16
	v_readlane_b32 s17, v252, 17
	v_cndmask_b32_e32 v66, v64, v66, vcc
	v_lshlrev_b32_e32 v226, 2, v66
	v_xor_b32_e32 v66, 4, v64
	v_cmp_lt_i32_e32 vcc, v66, v65
	s_mov_b64 s[0:1], 0x2700000
	v_readlane_b32 s9, v252, 9
	v_cndmask_b32_e32 v66, v64, v66, vcc
	v_lshlrev_b32_e32 v227, 2, v66
	v_xor_b32_e32 v66, 8, v64
	v_cmp_lt_i32_e32 vcc, v66, v65
	v_readlane_b32 s10, v252, 10
	v_readlane_b32 s11, v252, 11
	v_cndmask_b32_e32 v66, v64, v66, vcc
	v_lshlrev_b32_e32 v228, 2, v66
	v_xor_b32_e32 v66, 16, v64
	v_cmp_lt_i32_e32 vcc, v66, v65
	v_readlane_b32 s12, v252, 12
	v_readlane_b32 s13, v252, 13
	v_cndmask_b32_e32 v66, v64, v66, vcc
	v_lshlrev_b32_e32 v229, 2, v66
	v_xor_b32_e32 v66, 32, v64
	v_cmp_lt_i32_e32 vcc, v66, v65
	v_mov_b32_e32 v65, v209
	v_readlane_b32 s14, v252, 14
	v_cndmask_b32_e32 v64, v64, v66, vcc
	v_lshlrev_b32_e32 v230, 2, v64
	v_add_u32_e32 v64, 0, v208
	v_add_u32_e32 v188, 0x18000, v64
	v_bfe_u32 v64, v224, 4, 1
	v_bfe_u32 v66, v224, 5, 1
	v_lshl_add_u32 v64, v64, 1, v66
	v_bfe_u32 v66, v224, 3, 1
	v_lshl_add_u32 v64, v66, 2, v64
	v_lshlrev_b32_e32 v64, 2, v64
	v_lshl_add_u64 v[216:217], s[16:17], 0, v[64:65]
	v_and_b32_e32 v226, 28, v64
	v_mov_b32_e32 v227, 0
	v_lshl_add_u64 v[226:227], s[16:17], 0, v[226:227]
	global_load_dword v225, v[226:227], off
	v_lshl_add_u64 v[64:65], s[30:31], 0, v[64:65]
	v_lshl_add_u64 v[218:219], v[64:65], 0, s[0:1]
	ds_read_b128 v[64:67], v188
	ds_read_b128 v[68:71], v188 offset:1024
	ds_read_b128 v[72:75], v188 offset:2048
	ds_read_b128 v[76:79], v188 offset:3072
	ds_read_b128 v[80:83], v188 offset:4096
	ds_read_b128 v[84:87], v188 offset:5120
	ds_read_b128 v[88:91], v188 offset:6144
	ds_read_b128 v[92:95], v188 offset:7168
	ds_read_b128 v[96:99], v188 offset:8192
	ds_read_b128 v[100:103], v188 offset:9216
	ds_read_b128 v[104:107], v188 offset:10240
	ds_read_b128 v[108:111], v188 offset:11264
	ds_read_b128 v[112:115], v188 offset:12288
	ds_read_b128 v[116:119], v188 offset:13312
	ds_read_b128 v[120:123], v188 offset:14336
	ds_read_b128 v[124:127], v188 offset:15360
	ds_read_b128 v[128:131], v188 offset:16384
	ds_read_b128 v[132:135], v188 offset:17408
	ds_read_b128 v[136:139], v188 offset:18432
	ds_read_b128 v[140:143], v188 offset:19456
	ds_read_b128 v[144:147], v188 offset:20480
	ds_read_b128 v[148:151], v188 offset:21504
	ds_read_b128 v[152:155], v188 offset:22528
	ds_read_b128 v[156:159], v188 offset:23552
	ds_read_b128 v[160:163], v188 offset:24576
	ds_read_b128 v[164:167], v188 offset:25600
	ds_read_b128 v[168:171], v188 offset:26624
	ds_read_b128 v[172:175], v188 offset:27648
	ds_read_b128 v[176:179], v188 offset:28672
	ds_read_b128 v[180:183], v188 offset:29696
	ds_read_b128 v[184:187], v188 offset:30720
	ds_read_b128 v[188:191], v188 offset:31744
	v_readlane_b32 s15, v252, 15
	v_readlane_b32 s18, v252, 18
	v_readlane_b32 s19, v252, 19
	v_readlane_b32 s20, v252, 20
	v_readlane_b32 s21, v252, 21
	v_readlane_b32 s22, v252, 22
	v_readlane_b32 s23, v252, 23
	v_mov_b32_e32 v211, v209
	s_lshl_b32 s3, s26, 4
	v_lshl_add_u64 v[212:213], s[8:9], 0, v[208:209]
	v_lshl_add_u64 v[214:215], s[24:25], 0, v[210:211]
	v_and_b32_e32 v229, 7, v224
	v_cmp_eq_u32_e32 vcc, 0, v229
	v_cmp_eq_u32_e64 s[8:9], 0, v224
	v_cmp_eq_u32_e64 s[10:11], 1, v224
	v_cmp_eq_u32_e64 s[12:13], 2, v224
	v_cmp_eq_u32_e64 s[14:15], 3, v224
	v_cmp_eq_u32_e64 s[16:17], 4, v224
	v_cmp_eq_u32_e64 s[18:19], 5, v224
	v_cmp_eq_u32_e64 s[20:21], 6, v224
	v_cmp_eq_u32_e64 s[22:23], 7, v224
	v_mov_b32_e32 v209, 0x358637bd
	s_mov_b32 s27, 0x800000
	s_mov_b32 s35, 0xbfb8aa3b
	s_mov_b32 s41, 0x3f2aaaab
	v_mov_b32_e32 v211, 0x3ecc95a3
	s_mov_b32 s52, 0x3f317218
	s_mov_b32 s53, 0x7f800000
	s_mov_b32 s54, 0x33800000
	v_mov_b32_e32 v220, 0x3f317218
	v_mov_b32_e32 v231, 0x7f800000
	v_mov_b32_e32 v232, 0x7fc00000
	v_mov_b32_e32 v233, 0xff800000
	s_mov_b32 s68, s86
	s_waitcnt vmcnt(0)
	s_branch .LBB0_113

.LBB0_115:
	s_waitcnt lgkmcnt(0)
	v_pk_mul_f32 v[226:227], v[60:61], v[60:61]
	v_pk_fma_f32 v[226:227], v[62:63], v[62:63], v[226:227]
	v_pk_fma_f32 v[226:227], v[56:57], v[56:57], v[226:227]
	v_pk_fma_f32 v[226:227], v[58:59], v[58:59], v[226:227]
	v_pk_fma_f32 v[226:227], v[52:53], v[52:53], v[226:227]
	v_pk_fma_f32 v[226:227], v[54:55], v[54:55], v[226:227]
	v_pk_fma_f32 v[226:227], v[48:49], v[48:49], v[226:227]
	v_pk_fma_f32 v[226:227], v[50:51], v[50:51], v[226:227]
	v_add_f32_e32 v221, v226, v227
	v_pk_mul_f32 v[234:235], v[60:61], v[64:65]
	v_pk_fma_f32 v[234:235], v[62:63], v[66:67], v[234:235]
	v_add_f32_dpp v221, v221, v221 quad_perm:[1,0,3,2] row_mask:0xf bank_mask:0xf
	v_pk_fma_f32 v[234:235], v[56:57], v[68:69], v[234:235]
	v_pk_fma_f32 v[234:235], v[58:59], v[70:71], v[234:235]
	v_pk_fma_f32 v[234:235], v[52:53], v[72:73], v[234:235]
	v_add_f32_dpp v221, v221, v221 quad_perm:[2,3,0,1] row_mask:0xf bank_mask:0xf
	v_pk_fma_f32 v[234:235], v[54:55], v[74:75], v[234:235]
	v_pk_fma_f32 v[234:235], v[48:49], v[76:77], v[234:235]
	v_pk_fma_f32 v[234:235], v[50:51], v[78:79], v[234:235]
	v_add_f32_dpp v221, v221, v221 row_half_mirror row_mask:0xf bank_mask:0xf
	v_add_f32_e32 v234, v234, v235
	v_pk_mul_f32 v[236:237], v[60:61], v[80:81]
	v_pk_fma_f32 v[236:237], v[62:63], v[82:83], v[236:237]
	v_add_f32_dpp v221, v221, v221 row_mirror row_mask:0xf bank_mask:0xf
	v_pk_fma_f32 v[236:237], v[56:57], v[84:85], v[236:237]
	v_pk_fma_f32 v[236:237], v[58:59], v[86:87], v[236:237]
	v_pk_fma_f32 v[236:237], v[52:53], v[88:89], v[236:237]
	v_mov_b32_e32 v222, v221
	v_pk_fma_f32 v[236:237], v[54:55], v[90:91], v[236:237]
	v_pk_fma_f32 v[236:237], v[48:49], v[92:93], v[236:237]
	v_pk_fma_f32 v[236:237], v[50:51], v[94:95], v[236:237]
	v_permlane16_swap_b32_e32 v222, v221
	v_add_f32_e32 v236, v236, v237
	v_pk_mul_f32 v[238:239], v[60:61], v[96:97]
	v_pk_fma_f32 v[238:239], v[62:63], v[98:99], v[238:239]
	v_add_f32_e32 v221, v221, v222
	v_pk_fma_f32 v[238:239], v[56:57], v[100:101], v[238:239]
	v_pk_fma_f32 v[238:239], v[58:59], v[102:103], v[238:239]
	v_pk_fma_f32 v[238:239], v[52:53], v[104:105], v[238:239]
	v_mov_b32_e32 v222, v221
	v_pk_fma_f32 v[238:239], v[54:55], v[106:107], v[238:239]
	v_pk_fma_f32 v[238:239], v[48:49], v[108:109], v[238:239]
	v_pk_fma_f32 v[238:239], v[50:51], v[110:111], v[238:239]
	v_permlane32_swap_b32_e32 v222, v221
	v_add_f32_e32 v238, v238, v239
	v_pk_mul_f32 v[240:241], v[60:61], v[112:113]
	v_pk_fma_f32 v[240:241], v[62:63], v[114:115], v[240:241]
	v_add_f32_e32 v221, v221, v222
	v_pk_fma_f32 v[240:241], v[56:57], v[116:117], v[240:241]
	v_pk_fma_f32 v[240:241], v[58:59], v[118:119], v[240:241]
	v_pk_fma_f32 v[240:241], v[52:53], v[120:121], v[240:241]
	v_fmamk_f32 v221, v221, 0x3a800000, v209
	v_pk_fma_f32 v[240:241], v[54:55], v[122:123], v[240:241]
	v_pk_fma_f32 v[240:241], v[48:49], v[124:125], v[240:241]
	v_pk_fma_f32 v[240:241], v[50:51], v[126:127], v[240:241]
	v_cmp_gt_f32_e64 s[0:1], s27, v221
	v_add_f32_e32 v240, v240, v241
	v_pk_mul_f32 v[242:243], v[60:61], v[128:129]
	v_pk_fma_f32 v[242:243], v[62:63], v[130:131], v[242:243]
	v_mul_f32_e32 v228, 0x4b800000, v221
	v_pk_fma_f32 v[242:243], v[56:57], v[132:133], v[242:243]
	v_pk_fma_f32 v[242:243], v[58:59], v[134:135], v[242:243]
	v_pk_fma_f32 v[242:243], v[52:53], v[136:137], v[242:243]
	v_cndmask_b32_e64 v221, v221, v228, s[0:1]
	v_pk_fma_f32 v[242:243], v[54:55], v[138:139], v[242:243]
	v_pk_fma_f32 v[242:243], v[48:49], v[140:141], v[242:243]
	v_pk_fma_f32 v[242:243], v[50:51], v[142:143], v[242:243]
	v_rsq_f32_e32 v221, v221
	v_add_f32_e32 v242, v242, v243
	v_pk_mul_f32 v[244:245], v[60:61], v[144:145]
	v_pk_fma_f32 v[244:245], v[62:63], v[146:147], v[244:245]
	v_mul_f32_e32 v222, 0x45800000, v221
	v_pk_fma_f32 v[244:245], v[56:57], v[148:149], v[244:245]
	v_pk_fma_f32 v[244:245], v[58:59], v[150:151], v[244:245]
	v_pk_fma_f32 v[244:245], v[52:53], v[152:153], v[244:245]
	v_cndmask_b32_e64 v222, v221, v222, s[0:1]
	v_pk_fma_f32 v[244:245], v[54:55], v[154:155], v[244:245]
	v_pk_fma_f32 v[244:245], v[48:49], v[156:157], v[244:245]
	v_pk_fma_f32 v[244:245], v[50:51], v[158:159], v[244:245]
	v_add_f32_e32 v244, v244, v245
	v_pk_mul_f32 v[246:247], v[60:61], v[160:161]
	v_pk_fma_f32 v[246:247], v[62:63], v[162:163], v[246:247]
	v_pk_fma_f32 v[246:247], v[56:57], v[164:165], v[246:247]
	v_pk_fma_f32 v[246:247], v[58:59], v[166:167], v[246:247]
	v_pk_fma_f32 v[246:247], v[52:53], v[168:169], v[246:247]
	v_pk_fma_f32 v[246:247], v[54:55], v[170:171], v[246:247]
	v_pk_fma_f32 v[246:247], v[48:49], v[172:173], v[246:247]
	v_pk_fma_f32 v[246:247], v[50:51], v[174:175], v[246:247]
	v_add_f32_e32 v246, v246, v247
	v_pk_mul_f32 v[248:249], v[60:61], v[176:177]
	v_pk_fma_f32 v[248:249], v[62:63], v[178:179], v[248:249]
	v_pk_fma_f32 v[248:249], v[56:57], v[180:181], v[248:249]
	v_pk_fma_f32 v[248:249], v[58:59], v[182:183], v[248:249]
	v_pk_fma_f32 v[248:249], v[52:53], v[184:185], v[248:249]
	v_pk_fma_f32 v[248:249], v[54:55], v[186:187], v[248:249]
	v_pk_fma_f32 v[248:249], v[48:49], v[188:189], v[248:249]
	v_pk_fma_f32 v[248:249], v[50:51], v[190:191], v[248:249]
	v_add_f32_e32 v248, v248, v249
	v_permlane32_swap_b32_e32 v234, v236
	v_permlane32_swap_b32_e32 v238, v240
	v_permlane32_swap_b32_e32 v242, v244
	v_permlane32_swap_b32_e32 v246, v248
	v_add_f32_e32 v234, v234, v236
	v_add_f32_e32 v238, v238, v240
	v_add_f32_e32 v242, v242, v244
	v_add_f32_e32 v246, v246, v248
	v_permlane16_swap_b32_e32 v234, v238
	s_nop 0
	v_permlane16_swap_b32_e32 v242, v246
	v_add_f32_e32 v234, v234, v238
	v_add_f32_e32 v242, v242, v246
	s_ashr_i32 s69, s68, 31
	v_pk_mul_f32 v[62:63], v[18:19], v[62:63]
	v_add_f32_dpp v229, v234, v234 row_ror:8 row_mask:0xf bank_mask:0x3
	v_pk_mul_f32 v[60:61], v[16:17], v[60:61]
	v_pk_mul_f32 v[58:59], v[22:23], v[58:59]
	v_pk_mul_f32 v[56:57], v[20:21], v[56:57]
	v_add_f32_dpp v229, v242, v242 row_ror:8 row_mask:0xf bank_mask:0xc
	v_pk_mul_f32 v[54:55], v[26:27], v[54:55]
	v_pk_mul_f32 v[52:53], v[24:25], v[52:53]
	v_pk_mul_f32 v[50:51], v[30:31], v[50:51]
	v_add_f32_dpp v229, v229, v229 row_half_mirror row_mask:0xf bank_mask:0xf
	v_pk_mul_f32 v[48:49], v[28:29], v[48:49]
	s_lshl_b64 s[0:1], s[68:69], 11
	v_pk_mul_f32 v[62:63], v[62:63], v[222:223] op_sel_hi:[1,0]
	v_add_f32_dpp v229, v229, v229 quad_perm:[2,3,0,1] row_mask:0xf bank_mask:0xf
	v_pk_mul_f32 v[60:61], v[60:61], v[222:223] op_sel_hi:[1,0]
	v_pk_mul_f32 v[58:59], v[58:59], v[222:223] op_sel_hi:[1,0]
	v_pk_mul_f32 v[56:57], v[56:57], v[222:223] op_sel_hi:[1,0]
	v_add_f32_dpp v229, v229, v229 quad_perm:[1,0,3,2] row_mask:0xf bank_mask:0xf
	v_pk_mul_f32 v[54:55], v[54:55], v[222:223] op_sel_hi:[1,0]
	v_pk_mul_f32 v[52:53], v[52:53], v[222:223] op_sel_hi:[1,0]
	v_pk_mul_f32 v[50:51], v[50:51], v[222:223] op_sel_hi:[1,0]
	v_pk_mul_f32 v[48:49], v[48:49], v[222:223] op_sel_hi:[1,0]
	v_lshl_add_u64 v[250:251], v[214:215], 0, s[0:1]
	v_cvt_pk_bf16_f32 v60, v60, v61
	v_cvt_pk_bf16_f32 v61, v62, v63
	v_cvt_pk_bf16_f32 v56, v56, v57
	v_cvt_pk_bf16_f32 v57, v58, v59
	v_cvt_pk_bf16_f32 v52, v52, v53
	v_cvt_pk_bf16_f32 v53, v54, v55
	v_cvt_pk_bf16_f32 v48, v48, v49
	v_cvt_pk_bf16_f32 v49, v50, v51
	global_store_dwordx2 v[250:251], v[60:61], off
	global_store_dwordx2 v[250:251], v[56:57], off offset:512
	global_store_dwordx2 v[250:251], v[52:53], off offset:1024
	global_store_dwordx2 v[250:251], v[48:49], off offset:1536
	s_and_saveexec_b64 s[70:71], vcc
	s_cbranch_execz .LBB0_112
	v_mul_f32_e32 v49, v222, v229
	s_lshl_b64 s[68:69], s[68:69], 5
	v_add_f32_e32 v48, v49, v225
	v_mul_f32_e64 v49, |v48|, s35
	v_exp_f32_e32 v62, v49
	v_min_f32_e32 v63, 0, v48
	v_add_f32_e32 v50, 1.0, v62
	v_add_f32_e32 v51, -1.0, v50
	v_frexp_mant_f32_e32 v52, v50
	v_cvt_f64_f32_e32 v[48:49], v50
	v_sub_f32_e32 v53, v51, v50
	v_frexp_exp_i32_f64_e32 v48, v[48:49]
	v_cmp_gt_f32_e64 s[0:1], s41, v52
	v_sub_f32_e32 v51, v62, v51
	v_add_f32_e32 v49, 1.0, v53
	v_subbrev_co_u32_e64 v48, s[0:1], 0, v48, s[0:1]
	v_add_f32_e32 v49, v51, v49
	v_sub_u32_e32 v51, 0, v48
	v_ldexp_f32 v50, v50, v51
	v_add_f32_e32 v52, -1.0, v50
	v_add_f32_e32 v53, 1.0, v50
	v_ldexp_f32 v49, v49, v51
	v_add_f32_e32 v51, 1.0, v52
	v_add_f32_e32 v54, -1.0, v53
	v_sub_f32_e32 v51, v50, v51
	v_sub_f32_e32 v50, v50, v54
	v_add_f32_e32 v54, v49, v51
	v_add_f32_e32 v49, v49, v50
	v_add_f32_e32 v56, v53, v49
	v_rcp_f32_e32 v57, v56
	v_add_f32_e32 v51, v52, v54
	v_sub_f32_e32 v52, v51, v52
	v_sub_f32_e32 v50, v56, v53
	v_mul_f32_e32 v59, v51, v57
	v_sub_f32_e32 v58, v54, v52
	v_mul_f32_e32 v52, v56, v59
	v_sub_f32_e32 v49, v49, v50
	v_fma_f32 v54, v59, v56, -v52
	v_fmac_f32_e32 v54, v59, v49
	v_add_f32_e32 v50, v52, v54
	v_sub_f32_e32 v53, v51, v50
	v_mov_b32_e32 v55, v50
	v_pk_add_f32 v[50:51], v[50:51], v[52:53] neg_lo:[0,1] neg_hi:[0,1]
	v_cvt_f32_i32_e32 v48, v48
	v_pk_add_f32 v[50:51], v[50:51], v[54:55] neg_lo:[0,1] neg_hi:[0,1]
	v_cmp_neq_f32_e64 s[0:1], s53, v62
	v_add_f32_e32 v51, v58, v51
	v_add_f32_e32 v50, v50, v51
	v_add_f32_e32 v51, v53, v50
	v_mul_f32_e32 v55, v57, v51
	v_mul_f32_e32 v52, v56, v55
	v_sub_f32_e32 v53, v53, v51
	v_add_f32_e32 v60, v59, v55
	v_fma_f32 v54, v55, v56, -v52
	v_add_f32_e32 v58, v50, v53
	v_sub_f32_e32 v50, v60, v59
	v_fmac_f32_e32 v54, v55, v49
	v_sub_f32_e32 v49, v55, v50
	v_add_f32_e32 v50, v52, v54
	v_sub_f32_e32 v53, v51, v50
	v_mov_b32_e32 v55, v50
	v_pk_add_f32 v[50:51], v[50:51], v[52:53] neg_lo:[0,1] neg_hi:[0,1]
	s_nop 0
	v_pk_add_f32 v[50:51], v[50:51], v[54:55] neg_lo:[0,1] neg_hi:[0,1]
	s_nop 0
	v_add_f32_e32 v51, v58, v51
	v_add_f32_e32 v50, v50, v51
	v_add_f32_e32 v50, v53, v50
	v_mul_f32_e32 v50, v57, v50
	v_add_f32_e32 v49, v49, v50
	v_add_f32_e32 v50, v60, v49
	v_mul_f32_e32 v52, v50, v50
	v_sub_f32_e32 v53, v50, v60
	v_fmamk_f32 v54, v52, 0x3e9b6dac, v211
	v_sub_f32_e32 v53, v49, v53
	v_mul_f32_e32 v49, v50, v52
	v_fmaak_f32 v221, v52, v54, 0x3f2aaada
	v_ldexp_f32 v55, v53, 1
	v_pk_mul_f32 v[52:53], v[48:49], v[220:221]
	v_ldexp_f32 v51, v50, 1
	v_fma_f32 v50, v48, s52, -v52
	v_fmac_f32_e32 v50, 0xb102e308, v48
	v_pk_add_f32 v[48:49], v[52:53], v[50:51]
	v_mov_b32_e32 v54, v52
	v_sub_f32_e32 v58, v49, v51
	v_pk_add_f32 v[56:57], v[48:49], v[52:53] neg_lo:[0,1] neg_hi:[0,1]
	v_sub_f32_e32 v52, v53, v58
	v_add_f32_e32 v55, v55, v52
	v_pk_add_f32 v[52:53], v[48:49], v[54:55]
	v_mov_b32_e32 v51, v48
	v_mov_b32_e32 v57, v53
	v_pk_add_f32 v[60:61], v[50:51], v[56:57] neg_lo:[0,1] neg_hi:[0,1]
	v_pk_add_f32 v[50:51], v[50:51], v[56:57]
	v_mov_b32_e32 v59, v48
	v_pk_add_f32 v[56:57], v[50:51], v[48:49] op_sel:[1,0] op_sel_hi:[0,1] neg_lo:[0,1] neg_hi:[0,1]
	v_mov_b32_e32 v58, v55
	v_mov_b32_e32 v54, v53
	v_mov_b32_e32 v55, v51
	v_pk_mov_b32 v[48:49], v[48:49], v[56:57] op_sel:[1,0]
	v_pk_add_f32 v[52:53], v[52:53], v[56:57] op_sel_hi:[1,0] neg_lo:[0,1] neg_hi:[0,1]
	v_pk_add_f32 v[48:49], v[54:55], v[48:49] neg_lo:[0,1] neg_hi:[0,1]
	v_mov_b32_e32 v52, v60
	v_pk_add_f32 v[48:49], v[58:59], v[48:49] neg_lo:[0,1] neg_hi:[0,1]
	v_mov_b32_e32 v61, v51
	v_pk_add_f32 v[52:53], v[52:53], v[48:49]
	s_nop 0
	v_pk_add_f32 v[54:55], v[52:53], v[52:53] op_sel:[0,1] op_sel_hi:[1,0]
	s_nop 0
	v_pk_add_f32 v[50:51], v[50:51], v[54:55] op_sel:[1,0] op_sel_hi:[0,1]
	v_mov_b32_e32 v53, v50
	v_mov_b32_e32 v49, v54
	v_pk_add_f32 v[54:55], v[52:53], v[60:61] neg_lo:[0,1] neg_hi:[0,1]
	s_nop 0
	v_sub_f32_e32 v51, v52, v54
	v_pk_add_f32 v[48:49], v[48:49], v[54:55] neg_lo:[0,1] neg_hi:[0,1]
	v_sub_f32_e32 v51, v60, v51
	v_add_f32_e32 v48, v48, v51
	v_add_f32_e32 v48, v48, v49
	v_add_f32_e32 v48, v50, v48
	v_cndmask_b32_e64 v48, v231, v48, s[0:1]
	v_cmp_ngt_f32_e64 s[0:1], -1.0, v62
	s_nop 1
	v_cndmask_b32_e64 v48, v232, v48, s[0:1]
	v_cmp_neq_f32_e64 s[0:1], -1.0, v62
	s_nop 1
	v_cndmask_b32_e64 v48, v233, v48, s[0:1]
	v_cmp_lt_f32_e64 s[0:1], |v62|, s54
	s_nop 1
	v_cndmask_b32_e64 v48, v48, v62, s[0:1]
	v_sub_f32_e32 v50, v63, v48
	v_lshl_add_u64 v[48:49], v[218:219], 0, s[68:69]
	global_store_dword v[48:49], v50, off
	s_branch .LBB0_112
